# FFN1 LDS-DMA main loop with three LDS buffers (DMA two stages ahead, counted vmcnt before the barrier), finer lgkmcnt waits
# baseline (speedup 1.0000x reference)
; DI int TIDX() { int t = threadIdx.x; asm volatile("" : "+v"(t)); return t; }
; template <class BR>
; DI void gemm_tile_w(const h16* __restrict__ A, int lda, const h16* __restrict__ B, int ldb, BR brow, int K, f32x16 (&acc)[4][2], h16* sm) {
;   const int tid = TIDX(), lane = tid & 63, w = tid >> 6, wm = w >> 1, wn = w & 1, r = lane & 31, hh = lane >> 5;
;   const unsigned ao = (unsigned)(tid >> 2) * (unsigned)lda + (unsigned)(tid & 3) * 8u;
;   const unsigned bo0 = (unsigned)brow(tid >> 2) * (unsigned)ldb + (unsigned)(tid & 3) * 8u;
;   const unsigned bo1 = (unsigned)brow((tid >> 2) + 64) * (unsigned)ldb + (unsigned)(tid & 3) * 8u;
;   const h16* ag = A;
;   const h16* bg = B;
;   u32x4 ra0[4], rb0[2], ra1[4], rb1[2];
; #pragma unroll
;   for (int i = 0; i < 4; ++i) ra0[i] = *(const u32x4*)(ag + (ao + (unsigned)i * 64u * (unsigned)lda));
;   rb0[0] = *(const u32x4*)(bg + bo0);
;   rb0[1] = *(const u32x4*)(bg + bo1);
;   ag += 32; bg += 32;
; #pragma unroll
;   for (int i = 0; i < 4; ++i) ra1[i] = *(const u32x4*)(ag + (ao + (unsigned)i * 64u * (unsigned)lda));
;   rb1[0] = *(const u32x4*)(bg + bo0);
;   rb1[1] = *(const u32x4*)(bg + bo1);
;   const int nk = K >> 5;
;   const int wofs = (tid >> 2) * LS2 + (tid & 3) * 8;
.LBB0_71:
	s_mul_hi_i32 s12, s22, 0x2e8ba2e9
	s_lshr_b32 s13, s12, 31
	s_ashr_i32 s12, s12, 6
	s_add_i32 s12, s12, s13
	s_lshl_b32 s14, s12, 3
	s_sub_i32 s13, s21, s14
	s_min_i32 s15, s13, 8
	s_abs_i32 s13, s15
	v_cvt_f32_u32_e32 v0, s13
	s_sub_i32 s18, 0, s13
	s_mulk_i32 s12, 0xfea0
	s_add_i32 s12, s12, s22
	v_rcp_iflag_f32_e32 v0, v0
	s_abs_i32 s16, s12
	s_xor_b32 s17, s12, s15
	s_ashr_i32 s17, s17, 31
	v_mul_f32_e32 v0, 0x4f7ffffe, v0
	v_cvt_u32_f32_e32 v0, v0
	s_nop 0
	v_readfirstlane_b32 s19, v0
	s_mul_i32 s18, s18, s19
	s_mul_hi_u32 s18, s19, s18
	s_add_i32 s19, s19, s18
	s_mul_hi_u32 s18, s16, s19
	s_mul_i32 s19, s18, s13
	s_sub_i32 s16, s16, s19
	s_add_i32 s26, s18, 1
	s_sub_i32 s19, s16, s13
	s_cmp_ge_u32 s16, s13
	s_cselect_b32 s18, s26, s18
	s_cselect_b32 s16, s19, s16
	s_add_i32 s19, s18, 1
	s_cmp_ge_u32 s16, s13
	s_cselect_b32 s13, s19, s18
	s_xor_b32 s13, s13, s17
	s_sub_i32 s13, s13, s17
	s_add_i32 s14, s14, s38
	s_mul_i32 s15, s15, s13
	s_add_i32 s14, s14, s12
	s_sub_i32 s12, s14, s15
	s_cmp_ge_i32 s12, s20
	s_cbranch_scc1 .LBB0_70
	v_mov_b32_e32 v18, v203
	s_lshl_b32 s26, s13, 6
	s_lshl_b32 s12, s12, 8
	v_ashrrev_i32_e32 v19, 2, v18
	v_bfe_i32 v2, v18, 7, 1
	v_and_b32_e32 v2, 0xb00, v2
	v_lshrrev_b32_e32 v3, 3, v18
	v_and_or_b32 v4, v19, 31, s26
	v_and_b32_e32 v3, 0x3fffe0, v3
	v_add_u32_e32 v2, v2, v4
	v_add_u32_e32 v10, v2, v3
	v_add_u32_e32 v3, 64, v19
	s_ashr_i32 s13, s12, 31
	v_lshlrev_b32_e32 v0, 3, v18
	v_lshrrev_b32_e32 v3, 1, v3
	s_lshl_b64 s[14:15], s[12:13], 11
	v_and_b32_e32 v20, 24, v0
	v_bfe_u32 v21, v18, 4, 2
	v_lshlrev_b32_e32 v21, 3, v21
	v_xor_b32_e32 v20, v20, v21
	v_and_b32_e32 v3, 0x3fffe0, v3
	s_add_u32 s14, s24, s14
	v_add_u32_e32 v11, v2, v3
	v_lshl_or_b32 v210, v10, 10, v20
	v_mov_b32_e32 v211, v1
	s_addc_u32 s15, s25, s15
	v_lshl_or_b32 v0, v19, 10, v20
	v_lshl_or_b32 v212, v11, 10, v20
	v_lshlrev_b64 v[10:11], 1, v[210:211]
	v_mov_b32_e32 v213, v1
	v_lshl_add_u64 v[2:3], v[0:1], 1, s[14:15]
	v_add_u32_e32 v204, 0x10000, v0
	v_mov_b32_e32 v205, v1
	v_add_u32_e32 v206, 0x20000, v0
	v_mov_b32_e32 v207, v1
	v_add_u32_e32 v208, 0x30000, v0
	v_mov_b32_e32 v209, v1
	v_lshl_add_u64 v[12:13], s[6:7], 0, v[10:11]
	v_lshlrev_b64 v[14:15], 1, v[212:213]
	v_lshl_add_u64 v[4:5], v[204:205], 1, s[14:15]
	v_lshl_add_u64 v[6:7], v[206:207], 1, s[14:15]
	v_lshl_add_u64 v[8:9], v[208:209], 1, s[14:15]
	v_lshl_add_u64 v[16:17], s[6:7], 0, v[14:15]
	v_readfirstlane_b32 s18, v203
	s_nop 3
	s_lshr_b32 s18, s18, 6
	s_lshl_b32 s18, s18, 10
	v_and_b32_e32 v136, 31, v203
	v_bfe_u32 v137, v203, 5, 1
	v_bfe_u32 v138, v203, 2, 2
	v_xor_b32_e32 v137, v137, v138
	v_lshlrev_b32_e32 v137, 4, v137
	v_lshl_or_b32 v136, v136, 6, v137
	v_lshrrev_b32_e32 v138, 7, v203
	v_lshl_add_u32 v130, v138, 13, v136
	v_bfe_u32 v138, v203, 6, 1
	v_lshl_add_u32 v132, v138, 12, v136
	v_add_u32_e32 v132, 0x4000, v132
	v_xor_b32_e32 v131, 32, v130
	v_xor_b32_e32 v133, 32, v132
	s_mov_b64 s[16:17], s[6:7]
	s_add_u32 m0, s18, 0x0
	v_lshl_add_u64 v[134:135], v[0:1], 1, s[14:15]
	global_load_lds_dwordx4 v[134:135], off
	s_add_u32 m0, s18, 0x1000
	v_lshl_add_u64 v[134:135], v[204:205], 1, s[14:15]
	global_load_lds_dwordx4 v[134:135], off
	s_add_u32 m0, s18, 0x2000
	v_lshl_add_u64 v[134:135], v[206:207], 1, s[14:15]
	global_load_lds_dwordx4 v[134:135], off
	s_add_u32 m0, s18, 0x3000
	v_lshl_add_u64 v[134:135], v[208:209], 1, s[14:15]
	global_load_lds_dwordx4 v[134:135], off
	s_add_u32 m0, s18, 0x4000
	v_lshl_add_u64 v[134:135], v[210:211], 1, s[16:17]
	global_load_lds_dwordx4 v[134:135], off
	s_add_u32 m0, s18, 0x5000
	v_lshl_add_u64 v[134:135], v[212:213], 1, s[16:17]
	global_load_lds_dwordx4 v[134:135], off
	s_add_u32 s14, s14, 64
	s_addc_u32 s15, s15, 0
	s_add_u32 s16, s16, 64
	s_addc_u32 s17, s17, 0
	s_add_u32 m0, s18, 0x6000
	v_lshl_add_u64 v[134:135], v[0:1], 1, s[14:15]
	global_load_lds_dwordx4 v[134:135], off
	s_add_u32 m0, s18, 0x7000
	v_lshl_add_u64 v[134:135], v[204:205], 1, s[14:15]
	global_load_lds_dwordx4 v[134:135], off
	s_add_u32 m0, s18, 0x8000
	v_lshl_add_u64 v[134:135], v[206:207], 1, s[14:15]
	global_load_lds_dwordx4 v[134:135], off
	s_add_u32 m0, s18, 0x9000
	v_lshl_add_u64 v[134:135], v[208:209], 1, s[14:15]
	global_load_lds_dwordx4 v[134:135], off
	s_add_u32 m0, s18, 0xa000
	v_lshl_add_u64 v[134:135], v[210:211], 1, s[16:17]
	global_load_lds_dwordx4 v[134:135], off
	s_add_u32 m0, s18, 0xb000
	v_lshl_add_u64 v[134:135], v[212:213], 1, s[16:17]
	global_load_lds_dwordx4 v[134:135], off
	s_add_u32 s14, s14, 64
	s_addc_u32 s15, s15, 0
	s_add_u32 s16, s16, 64
	s_addc_u32 s17, s17, 0
	v_mov_b32_e32 v2, 0
	s_mov_b32 s13, 0
	v_mov_b32_e32 v3, v2
	v_mov_b32_e32 v4, v2
	v_mov_b32_e32 v5, v2
	v_mov_b32_e32 v6, v2
	v_mov_b32_e32 v7, v2
	v_mov_b32_e32 v8, v2
	v_mov_b32_e32 v9, v2
	v_mov_b32_e32 v10, v2
	v_mov_b32_e32 v11, v2
	v_mov_b32_e32 v12, v2
	v_mov_b32_e32 v13, v2
	v_mov_b32_e32 v14, v2
	v_mov_b32_e32 v15, v2
	v_mov_b32_e32 v16, v2
	v_mov_b32_e32 v17, v2
	v_mov_b32_e32 v18, v2
	v_mov_b32_e32 v19, v2
	v_mov_b32_e32 v20, v2
	v_mov_b32_e32 v21, v2
	v_mov_b32_e32 v22, v2
	v_mov_b32_e32 v23, v2
	v_mov_b32_e32 v24, v2
	v_mov_b32_e32 v25, v2
	v_mov_b32_e32 v26, v2
	v_mov_b32_e32 v27, v2
	v_mov_b32_e32 v28, v2
	v_mov_b32_e32 v29, v2
	v_mov_b32_e32 v30, v2
	v_mov_b32_e32 v31, v2
	v_mov_b32_e32 v32, v2
	v_mov_b32_e32 v33, v2
	v_mov_b32_e32 v34, v2
	v_mov_b32_e32 v35, v2
	v_mov_b32_e32 v36, v2
	v_mov_b32_e32 v37, v2
	v_mov_b32_e32 v38, v2
	v_mov_b32_e32 v39, v2
	v_mov_b32_e32 v40, v2
	v_mov_b32_e32 v41, v2
	v_mov_b32_e32 v42, v2
	v_mov_b32_e32 v43, v2
	v_mov_b32_e32 v44, v2
	v_mov_b32_e32 v45, v2
	v_mov_b32_e32 v46, v2
	v_mov_b32_e32 v47, v2
	v_mov_b32_e32 v48, v2
	v_mov_b32_e32 v49, v2
	s_waitcnt vmcnt(15)
; template <class BR>
; DI void gemm_tile_w(const h16* __restrict__ A, int lda, const h16* __restrict__ B, int ldb, BR brow, int K, f32x16 (&acc)[4][2], h16* sm) {
;     ...
;   for (int kt = 0; kt < nk; kt += 2) {
;     WIDE_HALF(ra0, rb0, 0, kt)
;     WIDE_HALF(ra1, rb1, 1, kt + 1)
;   }
	v_mov_b32_e32 v50, v2
	v_mov_b32_e32 v51, v2
	v_mov_b32_e32 v52, v2
	v_mov_b32_e32 v53, v2
	s_waitcnt vmcnt(14)
	v_mov_b32_e32 v54, v2
	v_mov_b32_e32 v55, v2
	v_mov_b32_e32 v56, v2
	v_mov_b32_e32 v57, v2
	s_waitcnt vmcnt(13)
	v_mov_b32_e32 v58, v2
	v_mov_b32_e32 v59, v2
	v_mov_b32_e32 v60, v2
	v_mov_b32_e32 v61, v2
	s_waitcnt vmcnt(12)
	v_mov_b32_e32 v62, v2
	v_mov_b32_e32 v63, v2
	v_mov_b32_e32 v64, v2
	v_mov_b32_e32 v65, v2
	v_mov_b32_e32 v66, v2
	v_mov_b32_e32 v67, v2
	v_mov_b32_e32 v68, v2
	v_mov_b32_e32 v69, v2
	v_mov_b32_e32 v70, v2
	v_mov_b32_e32 v71, v2
	v_mov_b32_e32 v72, v2
	v_mov_b32_e32 v73, v2
	v_mov_b32_e32 v74, v2
	v_mov_b32_e32 v75, v2
	v_mov_b32_e32 v76, v2
	v_mov_b32_e32 v77, v2
	v_mov_b32_e32 v78, v2
	v_mov_b32_e32 v79, v2
	v_mov_b32_e32 v80, v2
	v_mov_b32_e32 v81, v2
	v_mov_b32_e32 v82, v2
	v_mov_b32_e32 v83, v2
	v_mov_b32_e32 v84, v2
	v_mov_b32_e32 v85, v2
	v_mov_b32_e32 v86, v2
	v_mov_b32_e32 v87, v2
	v_mov_b32_e32 v88, v2
	v_mov_b32_e32 v89, v2
	v_mov_b32_e32 v90, v2
	v_mov_b32_e32 v91, v2
	v_mov_b32_e32 v92, v2
	v_mov_b32_e32 v93, v2
	v_mov_b32_e32 v94, v2
	v_mov_b32_e32 v95, v2
	v_mov_b32_e32 v96, v2
	v_mov_b32_e32 v97, v2
	v_mov_b32_e32 v98, v2
	v_mov_b32_e32 v99, v2
	v_mov_b32_e32 v100, v2
	v_mov_b32_e32 v101, v2
	v_mov_b32_e32 v102, v2
	v_mov_b32_e32 v103, v2
	v_mov_b32_e32 v104, v2
	v_mov_b32_e32 v105, v2
	v_mov_b32_e32 v106, v2
	v_mov_b32_e32 v107, v2
	v_mov_b32_e32 v108, v2
	v_mov_b32_e32 v109, v2
	v_mov_b32_e32 v110, v2
	v_mov_b32_e32 v111, v2
	v_mov_b32_e32 v112, v2
	v_mov_b32_e32 v113, v2
	v_mov_b32_e32 v114, v2
	v_mov_b32_e32 v115, v2
	v_mov_b32_e32 v116, v2
	v_mov_b32_e32 v117, v2
	v_mov_b32_e32 v118, v2
	v_mov_b32_e32 v119, v2
	v_mov_b32_e32 v120, v2
	v_mov_b32_e32 v121, v2
	v_mov_b32_e32 v122, v2
	v_mov_b32_e32 v123, v2
	v_mov_b32_e32 v124, v2
	v_mov_b32_e32 v125, v2
	v_mov_b32_e32 v126, v2
	v_mov_b32_e32 v127, v2
	v_mov_b32_e32 v128, v2
	v_mov_b32_e32 v129, v2
	s_waitcnt vmcnt(6)
	s_barrier
.Lfg_stage0:
	ds_read_b128 v[178:181], v130 offset:0
	ds_read_b128 v[182:185], v130 offset:2048
	ds_read_b128 v[186:189], v130 offset:4096
	ds_read_b128 v[190:193], v130 offset:6144
	ds_read_b128 v[194:197], v132 offset:0
	ds_read_b128 v[198:201], v132 offset:2048
	ds_read_b128 v[216:219], v131 offset:0
	ds_read_b128 v[220:223], v131 offset:2048
	ds_read_b128 v[226:229], v131 offset:4096
	ds_read_b128 v[230:233], v131 offset:6144
	ds_read_b128 v[234:237], v133 offset:0
	ds_read_b128 v[240:243], v133 offset:2048
	s_cmp_ge_u32 s13, 30
	s_cbranch_scc1 .Lfg_nl0
	s_add_u32 m0, s18, 0xc000
	v_lshl_add_u64 v[134:135], v[0:1], 1, s[14:15]
	global_load_lds_dwordx4 v[134:135], off
	s_add_u32 m0, s18, 0xd000
	v_lshl_add_u64 v[134:135], v[204:205], 1, s[14:15]
	global_load_lds_dwordx4 v[134:135], off
	s_add_u32 m0, s18, 0xe000
	v_lshl_add_u64 v[134:135], v[206:207], 1, s[14:15]
	global_load_lds_dwordx4 v[134:135], off
	s_add_u32 m0, s18, 0xf000
	v_lshl_add_u64 v[134:135], v[208:209], 1, s[14:15]
	global_load_lds_dwordx4 v[134:135], off
	s_add_u32 m0, s18, 0x10000
	v_lshl_add_u64 v[134:135], v[210:211], 1, s[16:17]
	global_load_lds_dwordx4 v[134:135], off
	s_add_u32 m0, s18, 0x11000
	v_lshl_add_u64 v[134:135], v[212:213], 1, s[16:17]
	global_load_lds_dwordx4 v[134:135], off
	s_add_u32 s14, s14, 64
	s_addc_u32 s15, s15, 0
	s_add_u32 s16, s16, 64
	s_addc_u32 s17, s17, 0
.Lfg_nl0:
	s_waitcnt lgkmcnt(7)
	v_mfma_f32_32x32x16_f16 v[114:129], v[178:181], v[194:197], v[114:129]
	s_waitcnt lgkmcnt(6)
	v_mfma_f32_32x32x16_f16 v[98:113], v[178:181], v[198:201], v[98:113]
	v_mfma_f32_32x32x16_f16 v[82:97], v[182:185], v[194:197], v[82:97]
	v_mfma_f32_32x32x16_f16 v[66:81], v[182:185], v[198:201], v[66:81]
	v_mfma_f32_32x32x16_f16 v[50:65], v[186:189], v[194:197], v[50:65]
	v_mfma_f32_32x32x16_f16 v[34:49], v[186:189], v[198:201], v[34:49]
	v_mfma_f32_32x32x16_f16 v[18:33], v[190:193], v[194:197], v[18:33]
	v_mfma_f32_32x32x16_f16 v[2:17], v[190:193], v[198:201], v[2:17]
	s_waitcnt lgkmcnt(1)
	v_mfma_f32_32x32x16_f16 v[114:129], v[216:219], v[234:237], v[114:129]
	s_waitcnt lgkmcnt(0)
	v_mfma_f32_32x32x16_f16 v[98:113], v[216:219], v[240:243], v[98:113]
	v_mfma_f32_32x32x16_f16 v[82:97], v[220:223], v[234:237], v[82:97]
	v_mfma_f32_32x32x16_f16 v[66:81], v[220:223], v[240:243], v[66:81]
	v_mfma_f32_32x32x16_f16 v[50:65], v[226:229], v[234:237], v[50:65]
	v_mfma_f32_32x32x16_f16 v[34:49], v[226:229], v[240:243], v[34:49]
	v_mfma_f32_32x32x16_f16 v[18:33], v[230:233], v[234:237], v[18:33]
	v_mfma_f32_32x32x16_f16 v[2:17], v[230:233], v[240:243], v[2:17]
	s_add_i32 s13, s13, 1
	s_cmp_ge_u32 s13, 32
	s_cbranch_scc1 .LBB0_69
	s_cmp_ge_u32 s13, 31
	s_cbranch_scc1 .Lfg_w0_0
	s_waitcnt vmcnt(6)
	s_branch .Lfg_w1_0

.Lfg_w1_0:
	s_barrier
.Lfg_stage1:
	ds_read_b128 v[178:181], v130 offset:24576
	ds_read_b128 v[182:185], v130 offset:26624
	ds_read_b128 v[186:189], v130 offset:28672
	ds_read_b128 v[190:193], v130 offset:30720
	ds_read_b128 v[194:197], v132 offset:24576
	ds_read_b128 v[198:201], v132 offset:26624
	ds_read_b128 v[216:219], v131 offset:24576
	ds_read_b128 v[220:223], v131 offset:26624
	ds_read_b128 v[226:229], v131 offset:28672
	ds_read_b128 v[230:233], v131 offset:30720
	ds_read_b128 v[234:237], v133 offset:24576
	ds_read_b128 v[240:243], v133 offset:26624
	s_cmp_ge_u32 s13, 30
	s_cbranch_scc1 .Lfg_nl1
	s_add_u32 m0, s18, 0x0
	v_lshl_add_u64 v[134:135], v[0:1], 1, s[14:15]
	global_load_lds_dwordx4 v[134:135], off
	s_add_u32 m0, s18, 0x1000
	v_lshl_add_u64 v[134:135], v[204:205], 1, s[14:15]
	global_load_lds_dwordx4 v[134:135], off
	s_add_u32 m0, s18, 0x2000
	v_lshl_add_u64 v[134:135], v[206:207], 1, s[14:15]
	global_load_lds_dwordx4 v[134:135], off
	s_add_u32 m0, s18, 0x3000
	v_lshl_add_u64 v[134:135], v[208:209], 1, s[14:15]
	global_load_lds_dwordx4 v[134:135], off
	s_add_u32 m0, s18, 0x4000
	v_lshl_add_u64 v[134:135], v[210:211], 1, s[16:17]
	global_load_lds_dwordx4 v[134:135], off
	s_add_u32 m0, s18, 0x5000
	v_lshl_add_u64 v[134:135], v[212:213], 1, s[16:17]
	global_load_lds_dwordx4 v[134:135], off
	s_add_u32 s14, s14, 64
	s_addc_u32 s15, s15, 0
	s_add_u32 s16, s16, 64
	s_addc_u32 s17, s17, 0

.Lfg_stage2:
	ds_read_b128 v[178:181], v130 offset:49152
	ds_read_b128 v[182:185], v130 offset:51200
	ds_read_b128 v[186:189], v130 offset:53248
	ds_read_b128 v[190:193], v130 offset:55296
	ds_read_b128 v[194:197], v132 offset:49152
	ds_read_b128 v[198:201], v132 offset:51200
	ds_read_b128 v[216:219], v131 offset:49152
	ds_read_b128 v[220:223], v131 offset:51200
	ds_read_b128 v[226:229], v131 offset:53248
	ds_read_b128 v[230:233], v131 offset:55296
	ds_read_b128 v[234:237], v133 offset:49152
	ds_read_b128 v[240:243], v133 offset:51200
	s_cmp_ge_u32 s13, 30
	s_cbranch_scc1 .Lfg_nl2
	s_add_u32 m0, s18, 0x6000
	v_lshl_add_u64 v[134:135], v[0:1], 1, s[14:15]
	global_load_lds_dwordx4 v[134:135], off
	s_add_u32 m0, s18, 0x7000
	v_lshl_add_u64 v[134:135], v[204:205], 1, s[14:15]
	global_load_lds_dwordx4 v[134:135], off
	s_add_u32 m0, s18, 0x8000
	v_lshl_add_u64 v[134:135], v[206:207], 1, s[14:15]
	global_load_lds_dwordx4 v[134:135], off
	s_add_u32 m0, s18, 0x9000
	v_lshl_add_u64 v[134:135], v[208:209], 1, s[14:15]
	global_load_lds_dwordx4 v[134:135], off
	s_add_u32 m0, s18, 0xa000
	v_lshl_add_u64 v[134:135], v[210:211], 1, s[16:17]
	global_load_lds_dwordx4 v[134:135], off
	s_add_u32 m0, s18, 0xb000
	v_lshl_add_u64 v[134:135], v[212:213], 1, s[16:17]
	global_load_lds_dwordx4 v[134:135], off
	s_add_u32 s14, s14, 64
	s_addc_u32 s15, s15, 0
	s_add_u32 s16, s16, 64
	s_addc_u32 s17, s17, 0

; template <class BR>
; DI void gemm_tile_w(const h16* __restrict__ A, int lda, const h16* __restrict__ B, int ldb, BR brow, int K, f32x16 (&acc)[4][2], h16* sm) {
;     ...
;   for (int kt = 0; kt < nk; kt += 2) {
;     WIDE_HALF(ra0, rb0, 0, kt)
;     WIDE_HALF(ra1, rb1, 1, kt + 1)
;   }
.Lfg_w1_2:
	s_barrier
	s_branch .Lfg_stage0
